# row_res main path: hoist all 12 loads of an iteration to loop top (v_mov copies at old sites)
# speedup vs baseline: 1.0117x; 1.0117x over previous
; __device__ __forceinline__ bf16* hrow16(unsigned char* ws, int r) { return (bf16*)(ws + WS_H16) + ((size_t)r << 10); }
; __device__ __forceinline__ void unpack8(const u32x4 w, float* v) { v[0] = bflo(w.x); v[1] = bfhi(w.x); v[2] = bflo(w.y); v[3] = bfhi(w.y); v[4] = bflo(w.z); v[5] = bfhi(w.z); v[6] = bflo(w.w); v[7] = bfhi(w.w); }
; __device__ __forceinline__ void row_res(KP kp, int gpost_in, int layer, bool has_next, int wid0, int row0, int row1, int b0, int nb, int tailp, bool pooled) {
;     ...
;     for (int base = row0 + ((int)blockIdx.x - b0) * 16 + wid; base < row1; base += nb * 16) {
;         float m[2][2][8], h[2][2][8]; float ss[2] = {0.f, 0.f};
; #pragma unroll
;         for (int r = 0; r < 2; ++r) { const int row = base + 8 * r; bf16* hp = hrow16(ws, row);
; #pragma unroll
;             for (int c = 0; c < 2; ++c) {
;                 if (tailp) { const bf16* t0 = (const bf16*)(ws + WS_MXT) + (size_t)(row - 128 * 256) * DM + c * 512 + lane * 8; unpack8(*(const u32x4*)t0, m[r][c]);
;                     for (int q = 1; q < tailp; ++q) { float m2[8]; unpack8(*(const u32x4*)(t0 + (size_t)q * 256 * 1024), m2);
; #pragma unroll
;                         for (int j = 0; j < 8; ++j) m[r][c][j] += m2[j]; } }
;                 else if (pooled) { const int t = row % LL, win = 2 << (c * 2 + (lane >> 5)), cnt = (t + 1) < win ? (t + 1) : win; const bf16* zp = MX + (size_t)row * DM + c * 512 + lane * 8;
;                     float z0[8], sum[8]; unpack8(*(const u32x4*)zp, z0);
; #pragma unroll
;                     for (int j = 0; j < 8; ++j) sum[j] = z0[j];
;                     for (int d = 1; d < cnt; ++d) { float zd[8]; unpack8(*(const u32x4*)(zp - (size_t)d * DM), zd);
; #pragma unroll
;                         for (int j = 0; j < 8; ++j) sum[j] += zd[j]; }
;                     const float inv = 1.0f / (float)cnt;
; #pragma unroll
;                     for (int j = 0; j < 8; ++j) m[r][c][j] = sum[j] * inv - z0[j]; }
;                 else { const u32x4 w = *(const u32x4*)(MX + (size_t)row * DM + c * 512 + lane * 8); unpack8(w, m[r][c]); }
;                 unpack8(*(const u32x4*)(hp + c * 512 + lane * 8), h[r][c]);
.LBB0_778:
	v_ashrrev_i32_e32 v39, 31, v38
	v_lshlrev_b64 v[2:3], 11, v[38:39]
	v_lshl_add_u64 v[4:5], v[44:45], 0, v[2:3]
	v_add_u32_e32 v116, 8, v38
	v_lshl_add_u64 v[170:171], v[42:43], 0, v[2:3]
	v_ashrrev_i32_e32 v117, 31, v116
	global_load_dwordx4 v[120:123], v[4:5], off
	global_load_dwordx4 v[124:127], v[4:5], off offset:1024
	v_lshlrev_b64 v[116:117], 11, v[116:117]
	global_load_dwordx4 v[136:139], v[170:171], off
	global_load_dwordx4 v[140:143], v[170:171], off offset:1024
	v_lshl_add_u64 v[168:169], v[44:45], 0, v[116:117]
	v_lshl_add_u64 v[172:173], v[42:43], 0, v[116:117]
	global_load_dwordx4 v[128:131], v[168:169], off
	global_load_dwordx4 v[132:135], v[168:169], off offset:1024
	global_load_dwordx4 v[144:147], v[172:173], off
	global_load_dwordx4 v[148:151], v[172:173], off offset:1024
	global_load_dwordx4 v[152:155], v[46:47], off
	global_load_dwordx4 v[156:159], v[46:47], off offset:16
	global_load_dwordx4 v[160:163], v[46:47], off offset:2048
	global_load_dwordx4 v[164:167], v[46:47], off offset:2064
	s_mov_b64 s[4:5], -1
	s_and_b64 vcc, exec, s[78:79]
	s_waitcnt vmcnt(0)
	v_mov_b64_e32 v[6:7], v[120:121]
	v_mov_b64_e32 v[8:9], v[122:123]
	v_lshlrev_b32_e32 v22, 16, v6
	s_waitcnt lgkmcnt(0)
	v_and_b32_e32 v23, 0xffff0000, v6
	v_lshlrev_b32_e32 v24, 16, v7
	v_and_b32_e32 v25, 0xffff0000, v7
	v_lshlrev_b32_e32 v26, 16, v8
	v_and_b32_e32 v27, 0xffff0000, v8
	v_lshlrev_b32_e32 v28, 16, v9
	v_and_b32_e32 v29, 0xffff0000, v9
	s_cbranch_vccz .LBB0_780
	s_mov_b64 s[4:5], 0

; __device__ __forceinline__ void unpack8(const u32x4 w, float* v) { v[0] = bflo(w.x); v[1] = bfhi(w.x); v[2] = bflo(w.y); v[3] = bfhi(w.y); v[4] = bflo(w.z); v[5] = bfhi(w.z); v[6] = bflo(w.w); v[7] = bfhi(w.w); }
; __device__ __forceinline__ void row_res(KP kp, int gpost_in, int layer, bool has_next, int wid0, int row0, int row1, int b0, int nb, int tailp, bool pooled) {
;     ...
;             for (int c = 0; c < 2; ++c) {
;                 if (tailp) { const bf16* t0 = (const bf16*)(ws + WS_MXT) + (size_t)(row - 128 * 256) * DM + c * 512 + lane * 8; unpack8(*(const u32x4*)t0, m[r][c]);
;                     for (int q = 1; q < tailp; ++q) { float m2[8]; unpack8(*(const u32x4*)(t0 + (size_t)q * 256 * 1024), m2);
; #pragma unroll
;                         for (int j = 0; j < 8; ++j) m[r][c][j] += m2[j]; } }
;                 else if (pooled) { const int t = row % LL, win = 2 << (c * 2 + (lane >> 5)), cnt = (t + 1) < win ? (t + 1) : win; const bf16* zp = MX + (size_t)row * DM + c * 512 + lane * 8;
;                     float z0[8], sum[8]; unpack8(*(const u32x4*)zp, z0);
; #pragma unroll
;                     for (int j = 0; j < 8; ++j) sum[j] = z0[j];
;                     for (int d = 1; d < cnt; ++d) { float zd[8]; unpack8(*(const u32x4*)(zp - (size_t)d * DM), zd);
; #pragma unroll
;                         for (int j = 0; j < 8; ++j) sum[j] += zd[j]; }
;                     const float inv = 1.0f / (float)cnt;
; #pragma unroll
;                     for (int j = 0; j < 8; ++j) m[r][c][j] = sum[j] * inv - z0[j]; }
;                 else { const u32x4 w = *(const u32x4*)(MX + (size_t)row * DM + c * 512 + lane * 8); unpack8(w, m[r][c]); }
;                 unpack8(*(const u32x4*)(hp + c * 512 + lane * 8), h[r][c]);
.LBB0_786:
	v_mov_b64_e32 v[6:7], v[124:125]
	v_mov_b64_e32 v[8:9], v[126:127]
	v_lshl_add_u64 v[60:61], v[42:43], 0, v[2:3]
	v_mov_b64_e32 v[2:3], v[136:137]
	v_mov_b64_e32 v[4:5], v[138:139]
	v_cndmask_b32_e64 v10, 0, 1, s[78:79]
	s_mov_b64 s[14:15], -1
	v_cmp_ne_u32_e64 s[4:5], 1, v10
	s_andn2_b64 vcc, exec, s[78:79]
	s_waitcnt vmcnt(1)
	v_lshlrev_b32_e32 v30, 16, v6
	v_and_b32_e32 v31, 0xffff0000, v6
	v_lshlrev_b32_e32 v32, 16, v7
	v_and_b32_e32 v33, 0xffff0000, v7
	v_lshlrev_b32_e32 v34, 16, v8
	v_and_b32_e32 v35, 0xffff0000, v8
	v_lshlrev_b32_e32 v36, 16, v9
	v_and_b32_e32 v37, 0xffff0000, v9
	s_cbranch_vccnz .LBB0_788
	s_mov_b64 s[14:15], 0

; __device__ __forceinline__ bf16* hrow16(unsigned char* ws, int r) { return (bf16*)(ws + WS_H16) + ((size_t)r << 10); }
; __device__ __forceinline__ void unpack8(const u32x4 w, float* v) { v[0] = bflo(w.x); v[1] = bfhi(w.x); v[2] = bflo(w.y); v[3] = bfhi(w.y); v[4] = bflo(w.z); v[5] = bfhi(w.z); v[6] = bflo(w.w); v[7] = bfhi(w.w); }
; __device__ __forceinline__ void row_res(KP kp, int gpost_in, int layer, bool has_next, int wid0, int row0, int row1, int b0, int nb, int tailp, bool pooled) {
;     ...
;         for (int r = 0; r < 2; ++r) { const int row = base + 8 * r; bf16* hp = hrow16(ws, row);
; #pragma unroll
;             for (int c = 0; c < 2; ++c) {
;                 if (tailp) { const bf16* t0 = (const bf16*)(ws + WS_MXT) + (size_t)(row - 128 * 256) * DM + c * 512 + lane * 8; unpack8(*(const u32x4*)t0, m[r][c]);
;                     for (int q = 1; q < tailp; ++q) { float m2[8]; unpack8(*(const u32x4*)(t0 + (size_t)q * 256 * 1024), m2);
; #pragma unroll
;                         for (int j = 0; j < 8; ++j) m[r][c][j] += m2[j]; } }
;                 else if (pooled) { const int t = row % LL, win = 2 << (c * 2 + (lane >> 5)), cnt = (t + 1) < win ? (t + 1) : win; const bf16* zp = MX + (size_t)row * DM + c * 512 + lane * 8;
;                     float z0[8], sum[8]; unpack8(*(const u32x4*)zp, z0);
; #pragma unroll
;                     for (int j = 0; j < 8; ++j) sum[j] = z0[j];
;                     for (int d = 1; d < cnt; ++d) { float zd[8]; unpack8(*(const u32x4*)(zp - (size_t)d * DM), zd);
; #pragma unroll
;                         for (int j = 0; j < 8; ++j) sum[j] += zd[j]; }
;                     const float inv = 1.0f / (float)cnt;
; #pragma unroll
;                     for (int j = 0; j < 8; ++j) m[r][c][j] = sum[j] * inv - z0[j]; }
;                 else { const u32x4 w = *(const u32x4*)(MX + (size_t)row * DM + c * 512 + lane * 8); unpack8(w, m[r][c]); }
;                 unpack8(*(const u32x4*)(hp + c * 512 + lane * 8), h[r][c]);
.LBB0_794:
	v_add_u32_e32 v62, 8, v38
	v_ashrrev_i32_e32 v63, 31, v62
	v_lshlrev_b64 v[10:11], 11, v[62:63]
	v_lshl_add_u64 v[12:13], v[44:45], 0, v[10:11]
	v_mov_b64_e32 v[14:15], v[128:129]
	v_mov_b64_e32 v[16:17], v[130:131]
	v_mov_b64_e32 v[6:7], v[140:141]
	v_mov_b64_e32 v[8:9], v[142:143]
	s_mov_b64 s[14:15], -1
	s_and_b64 vcc, exec, s[4:5]
	s_waitcnt vmcnt(1)
	v_lshlrev_b32_e32 v68, 16, v14
	v_and_b32_e32 v69, 0xffff0000, v14
	v_lshlrev_b32_e32 v70, 16, v15
	v_and_b32_e32 v71, 0xffff0000, v15
	v_lshlrev_b32_e32 v72, 16, v16
	v_and_b32_e32 v73, 0xffff0000, v16
	v_lshlrev_b32_e32 v74, 16, v17
	v_and_b32_e32 v75, 0xffff0000, v17
	s_cbranch_vccnz .LBB0_796
	s_mov_b64 s[14:15], 0

; __device__ __forceinline__ bf16* hrow16(unsigned char* ws, int r) { return (bf16*)(ws + WS_H16) + ((size_t)r << 10); }
; __device__ __forceinline__ void unpack8(const u32x4 w, float* v) { v[0] = bflo(w.x); v[1] = bfhi(w.x); v[2] = bflo(w.y); v[3] = bfhi(w.y); v[4] = bflo(w.z); v[5] = bfhi(w.z); v[6] = bflo(w.w); v[7] = bfhi(w.w); }
; __device__ __forceinline__ void row_res(KP kp, int gpost_in, int layer, bool has_next, int wid0, int row0, int row1, int b0, int nb, int tailp, bool pooled) {
;     ...
;         for (int r = 0; r < 2; ++r) { const int row = base + 8 * r; bf16* hp = hrow16(ws, row);
; #pragma unroll
;             for (int c = 0; c < 2; ++c) {
;                 if (tailp) { const bf16* t0 = (const bf16*)(ws + WS_MXT) + (size_t)(row - 128 * 256) * DM + c * 512 + lane * 8; unpack8(*(const u32x4*)t0, m[r][c]);
;                     for (int q = 1; q < tailp; ++q) { float m2[8]; unpack8(*(const u32x4*)(t0 + (size_t)q * 256 * 1024), m2);
; #pragma unroll
;                         for (int j = 0; j < 8; ++j) m[r][c][j] += m2[j]; } }
;                 else if (pooled) { const int t = row % LL, win = 2 << (c * 2 + (lane >> 5)), cnt = (t + 1) < win ? (t + 1) : win; const bf16* zp = MX + (size_t)row * DM + c * 512 + lane * 8;
;                     float z0[8], sum[8]; unpack8(*(const u32x4*)zp, z0);
; #pragma unroll
;                     for (int j = 0; j < 8; ++j) sum[j] = z0[j];
;                     for (int d = 1; d < cnt; ++d) { float zd[8]; unpack8(*(const u32x4*)(zp - (size_t)d * DM), zd);
; #pragma unroll
;                         for (int j = 0; j < 8; ++j) sum[j] += zd[j]; }
;                     const float inv = 1.0f / (float)cnt;
; #pragma unroll
;                     for (int j = 0; j < 8; ++j) m[r][c][j] = sum[j] * inv - z0[j]; }
;                 else { const u32x4 w = *(const u32x4*)(MX + (size_t)row * DM + c * 512 + lane * 8); unpack8(w, m[r][c]); }
;                 unpack8(*(const u32x4*)(hp + c * 512 + lane * 8), h[r][c]);
.LBB0_802:
	v_mov_b64_e32 v[16:17], v[132:133]
	v_mov_b64_e32 v[18:19], v[134:135]
	v_lshl_add_u64 v[66:67], v[42:43], 0, v[10:11]
	v_mov_b64_e32 v[10:11], v[144:145]
	v_mov_b64_e32 v[12:13], v[146:147]
	s_mov_b64 s[14:15], -1
	s_and_b64 vcc, exec, s[4:5]
	s_waitcnt vmcnt(1)
	v_lshlrev_b32_e32 v82, 16, v16
	v_and_b32_e32 v83, 0xffff0000, v16
	v_lshlrev_b32_e32 v80, 16, v17
	v_and_b32_e32 v81, 0xffff0000, v17
	v_lshlrev_b32_e32 v78, 16, v18
	v_and_b32_e32 v79, 0xffff0000, v18
	v_lshlrev_b32_e32 v76, 16, v19
	v_and_b32_e32 v77, 0xffff0000, v19
	s_cbranch_vccnz .LBB0_804
	s_mov_b64 s[14:15], 0

; __device__ __forceinline__ float lane_xchg_(float v, int srclane) { return __builtin_bit_cast(float, __builtin_amdgcn_ds_bpermute(srclane << 2, __builtin_bit_cast(int, v))); }
; __device__ __forceinline__ void unpack8(const u32x4 w, float* v) { v[0] = bflo(w.x); v[1] = bfhi(w.x); v[2] = bflo(w.y); v[3] = bfhi(w.y); v[4] = bflo(w.z); v[5] = bfhi(w.z); v[6] = bflo(w.w); v[7] = bfhi(w.w); }
; __device__ __forceinline__ void row_res(KP kp, int gpost_in, int layer, bool has_next, int wid0, int row0, int row1, int b0, int nb, int tailp, bool pooled) {
;     ...
;                 unpack8(*(const u32x4*)(hp + c * 512 + lane * 8), h[r][c]);
; #pragma unroll
;                 for (int j = 0; j < 8; ++j) ss[r] += m[r][c][j] * m[r][c][j]; } }
; #pragma unroll
;         for (int o = 32; o > 0; o >>= 1) { const float a = lane_xchg_(ss[0], lane ^ o), b = lane_xchg_(ss[1], lane ^ o); ss[0] += a; ss[1] += b; }
;         float s2[2] = {0.f, 0.f};
; #pragma unroll
;         for (int r = 0; r < 2; ++r) { const float rstd = 1.0f / sqrtf(ss[r] * (1.0f / DM) + NORM_EPS);
; #pragma unroll
;             for (int c = 0; c < 2; ++c) { const int col = c * 512 + lane * 8; const f32x4 ga = *(const f32x4*)(g_post + col), gb = *(const f32x4*)(g_post + col + 4);
; #pragma unroll
;                 for (int j = 0; j < 8; ++j) { h[r][c][j] += m[r][c][j] * rstd * (j < 4 ? ga[j & 3] : gb[j & 3]); s2[r] += h[r][c][j] * h[r][c][j]; } } }
.LBB0_810:
	s_waitcnt vmcnt(0)
	v_lshlrev_b32_e32 v84, 16, v10
	v_and_b32_e32 v85, 0xffff0000, v10
	v_lshlrev_b32_e32 v86, 16, v11
	v_and_b32_e32 v87, 0xffff0000, v11
	v_pk_mul_f32 v[10:11], v[22:23], v[22:23]
	v_lshlrev_b32_e32 v88, 16, v12
	v_and_b32_e32 v89, 0xffff0000, v12
	v_lshlrev_b32_e32 v90, 16, v13
	v_and_b32_e32 v91, 0xffff0000, v13
	v_pk_mul_f32 v[12:13], v[24:25], v[24:25]
	v_add_f32_e32 v10, v11, v10
	v_pk_mul_f32 v[14:15], v[68:69], v[68:69]
	v_add_f32_e32 v10, v12, v10
	v_pk_mul_f32 v[16:17], v[70:71], v[70:71]
	v_pk_mul_f32 v[108:109], v[26:27], v[26:27]
	v_add_f32_e32 v10, v13, v10
	v_add_f32_e32 v14, v15, v14
	v_add_f32_e32 v10, v108, v10
	v_add_f32_e32 v14, v16, v14
	v_pk_mul_f32 v[18:19], v[72:73], v[72:73]
	v_pk_mul_f32 v[110:111], v[28:29], v[28:29]
	v_add_f32_e32 v10, v109, v10
	v_add_f32_e32 v14, v17, v14
	v_add_f32_e32 v10, v110, v10
	v_add_f32_e32 v14, v18, v14
	v_pk_mul_f32 v[20:21], v[74:75], v[74:75]
	v_lshlrev_b32_e32 v92, 16, v6
	v_and_b32_e32 v93, 0xffff0000, v6
	v_lshlrev_b32_e32 v94, 16, v7
	v_and_b32_e32 v95, 0xffff0000, v7
	v_pk_mul_f32 v[6:7], v[30:31], v[30:31]
	v_add_f32_e32 v10, v111, v10
	v_add_f32_e32 v14, v19, v14
	v_add_f32_e32 v6, v10, v6
	v_add_f32_e32 v14, v20, v14
	v_lshlrev_b32_e32 v98, 16, v8
	v_and_b32_e32 v99, 0xffff0000, v8
	v_lshlrev_b32_e32 v96, 16, v9
	v_and_b32_e32 v97, 0xffff0000, v9
	v_pk_mul_f32 v[8:9], v[32:33], v[32:33]
	v_add_f32_e32 v6, v7, v6
	v_pk_mul_f32 v[108:109], v[82:83], v[82:83]
	v_add_f32_e32 v14, v21, v14
	v_add_f32_e32 v6, v8, v6
	v_add_f32_e32 v14, v14, v108
	v_pk_mul_f32 v[112:113], v[34:35], v[34:35]
	v_add_f32_e32 v6, v9, v6
	v_pk_mul_f32 v[110:111], v[80:81], v[80:81]
	v_add_f32_e32 v14, v109, v14
	v_add_f32_e32 v6, v112, v6
	v_add_f32_e32 v14, v110, v14
	v_pk_mul_f32 v[114:115], v[36:37], v[36:37]
	v_add_f32_e32 v6, v113, v6
	v_pk_mul_f32 v[112:113], v[78:79], v[78:79]
	v_add_f32_e32 v14, v111, v14
	v_add_f32_e32 v6, v114, v6
	v_add_f32_e32 v14, v112, v14
	v_add_f32_e32 v55, v115, v6
	v_pk_mul_f32 v[114:115], v[76:77], v[76:77]
	v_add_f32_e32 v14, v113, v14
	v_add_f32_e32 v14, v114, v14
	v_add_f32_e32 v14, v115, v14
	ds_bpermute_b32 v15, v101, v55
	ds_bpermute_b32 v16, v101, v14
	v_lshlrev_b32_e32 v6, 16, v2
	v_and_b32_e32 v7, 0xffff0000, v2
	v_lshlrev_b32_e32 v8, 16, v3
	s_waitcnt lgkmcnt(1)
	v_add_f32_e32 v15, v55, v15
	s_waitcnt lgkmcnt(0)
	v_add_f32_e32 v14, v14, v16
	ds_bpermute_b32 v16, v102, v15
	ds_bpermute_b32 v17, v102, v14
	v_and_b32_e32 v9, 0xffff0000, v3
	v_lshlrev_b32_e32 v10, 16, v4
	v_and_b32_e32 v11, 0xffff0000, v4
	s_waitcnt lgkmcnt(1)
	v_add_f32_e32 v15, v15, v16
	s_waitcnt lgkmcnt(0)
	v_add_f32_e32 v14, v14, v17
	ds_bpermute_b32 v16, v103, v15
	ds_bpermute_b32 v17, v103, v14
	v_lshlrev_b32_e32 v12, 16, v5
	v_and_b32_e32 v13, 0xffff0000, v5
	v_mov_b64_e32 v[2:3], v[148:149]
	v_mov_b64_e32 v[4:5], v[150:151]
	s_waitcnt lgkmcnt(1)
	v_add_f32_e32 v15, v15, v16
	s_waitcnt lgkmcnt(0)
	v_add_f32_e32 v14, v14, v17
	ds_bpermute_b32 v16, v104, v15
	ds_bpermute_b32 v17, v104, v14
	s_waitcnt lgkmcnt(1)
	v_add_f32_e32 v15, v15, v16
	s_waitcnt lgkmcnt(0)
	v_add_f32_e32 v14, v14, v17
	ds_bpermute_b32 v16, v105, v15
	ds_bpermute_b32 v17, v105, v14
	s_waitcnt lgkmcnt(1)
	v_add_f32_e32 v15, v15, v16
	s_waitcnt lgkmcnt(0)
	v_add_f32_e32 v14, v14, v17
	ds_bpermute_b32 v16, v106, v15
	ds_bpermute_b32 v17, v106, v14
	s_waitcnt lgkmcnt(1)
	v_add_f32_e32 v15, v15, v16
	s_waitcnt lgkmcnt(0)
	v_add_f32_e32 v55, v14, v17
	v_fmamk_f32 v14, v15, 0x3a800000, v242
	v_cmp_gt_f32_e32 vcc, s80, v14
	v_mul_f32_e32 v15, 0x4f800000, v14
	v_fmamk_f32 v55, v55, 0x3a800000, v242
	v_cndmask_b32_e32 v14, v14, v15, vcc
	v_sqrt_f32_e32 v15, v14
	v_mul_f32_e32 v59, 0x4f800000, v55
	v_add_u32_e32 v16, -1, v15
	v_fma_f32 v17, -v16, v15, v14
	v_cmp_ge_f32_e64 s[4:5], 0, v17
	v_add_u32_e32 v17, 1, v15
	s_nop 0
	v_cndmask_b32_e64 v16, v15, v16, s[4:5]
	v_fma_f32 v15, -v17, v15, v14
	v_cmp_lt_f32_e64 s[4:5], 0, v15
	s_nop 1
	v_cndmask_b32_e64 v15, v16, v17, s[4:5]
	v_mul_f32_e32 v16, 0x37800000, v15
	v_cndmask_b32_e32 v15, v15, v16, vcc
	v_cmp_class_f32_e32 vcc, v14, v243
	s_nop 1
	v_cndmask_b32_e32 v14, v15, v14, vcc
	v_div_scale_f32 v15, s[4:5], v14, v14, 1.0
	v_rcp_f32_e32 v16, v15
	s_nop 0
	v_fma_f32 v17, -v15, v16, 1.0
	v_fmac_f32_e32 v16, v17, v16
	v_div_scale_f32 v17, vcc, 1.0, v14, 1.0
	v_mul_f32_e32 v18, v17, v16
	v_fma_f32 v19, -v15, v18, v17
	v_fmac_f32_e32 v18, v19, v16
	v_fma_f32 v15, -v15, v18, v17
	v_div_fmas_f32 v15, v15, v16, v18
	v_div_fixup_f32 v100, v15, v14, 1.0
	v_mov_b64_e32 v[14:15], v[156:157]
	v_mov_b64_e32 v[16:17], v[158:159]
	v_mov_b64_e32 v[18:19], v[152:153]
	v_mov_b64_e32 v[20:21], v[154:155]
	v_pk_mul_f32 v[22:23], v[22:23], v[100:101] op_sel_hi:[1,0]
	v_cmp_gt_f32_e32 vcc, s80, v55
	v_pk_mul_f32 v[30:31], v[30:31], v[100:101] op_sel_hi:[1,0]
	v_pk_mul_f32 v[32:33], v[32:33], v[100:101] op_sel_hi:[1,0]
	v_cndmask_b32_e32 v55, v55, v59, vcc
	v_sqrt_f32_e32 v59, v55
	v_pk_mul_f32 v[34:35], v[34:35], v[100:101] op_sel_hi:[1,0]
	v_pk_mul_f32 v[36:37], v[36:37], v[100:101] op_sel_hi:[1,0]
	v_add_u32_e32 v65, -1, v59
	s_waitcnt vmcnt(0)
; __device__ __forceinline__ unsigned pk2(float lo, float hi) { const pk_f32x2 v = {lo, hi}; const pk_bf16x2 b = __builtin_convertvector(v, pk_bf16x2); return __builtin_bit_cast(unsigned, b); }
; __device__ __forceinline__ float lane_xchg_(float v, int srclane) { return __builtin_bit_cast(float, __builtin_amdgcn_ds_bpermute(srclane << 2, __builtin_bit_cast(int, v))); }
; __device__ __forceinline__ void row_res(KP kp, int gpost_in, int layer, bool has_next, int wid0, int row0, int row1, int b0, int nb, int tailp, bool pooled) {
;     ...
;         for (int r = 0; r < 2; ++r) { const float rstd = 1.0f / sqrtf(ss[r] * (1.0f / DM) + NORM_EPS);
; #pragma unroll
;             for (int c = 0; c < 2; ++c) { const int col = c * 512 + lane * 8; const f32x4 ga = *(const f32x4*)(g_post + col), gb = *(const f32x4*)(g_post + col + 4);
; #pragma unroll
;                 for (int j = 0; j < 8; ++j) { h[r][c][j] += m[r][c][j] * rstd * (j < 4 ? ga[j & 3] : gb[j & 3]); s2[r] += h[r][c][j] * h[r][c][j]; } } }
;         if (has_next) {
; #pragma unroll
;             for (int o = 32; o > 0; o >>= 1) { const float a = lane_xchg_(s2[0], lane ^ o), b = lane_xchg_(s2[1], lane ^ o); s2[0] += a; s2[1] += b; }
; #pragma unroll
;             for (int r = 0; r < 2; ++r) { const int row = base + 8 * r; bf16* hp = hrow16(ws, row);
; #pragma unroll
;                 for (int c = 0; c < 2; ++c) { u32x4 hw; hw.x = pk2(h[r][c][0], h[r][c][1]); hw.y = pk2(h[r][c][2], h[r][c][3]); hw.z = pk2(h[r][c][4], h[r][c][5]); hw.w = pk2(h[r][c][6], h[r][c][7]);
;                     *(u32x4*)(hp + c * 512 + lane * 8) = hw; }
;                 if (lane == 0) rsd[row] = 1.0f / sqrtf(s2[r] * (1.0f / DM) + NORM_EPS); }
;         } else {
; #pragma unroll
;             for (int r = 0; r < 2; ++r) { const int row = base + 8 * r; const int b = row / LL, t = row - b * LL;
;                 if (t >= NMETA) { float* op = out + (((size_t)b * SEQ + (t - NMETA)) << 10);
; #pragma unroll
;                     for (int c = 0; c < 2; ++c) { const int col = c * 512 + lane * 8;
;                         __builtin_nontemporal_store((f32x4){h[r][c][0], h[r][c][1], h[r][c][2], h[r][c][3]}, (f32x4*)(op + col)); __builtin_nontemporal_store((f32x4){h[r][c][4], h[r][c][5], h[r][c][6], h[r][c][7]}, (f32x4*)(op + col + 4)); } } }
	v_pk_fma_f32 v[6:7], v[18:19], v[22:23], v[6:7]
	v_pk_mul_f32 v[22:23], v[24:25], v[100:101] op_sel_hi:[1,0]
	s_nop 0
	v_pk_fma_f32 v[8:9], v[20:21], v[22:23], v[8:9]
	v_pk_mul_f32 v[22:23], v[26:27], v[100:101] op_sel_hi:[1,0]
	s_nop 0
	v_pk_fma_f32 v[10:11], v[14:15], v[22:23], v[10:11]
	v_pk_mul_f32 v[22:23], v[28:29], v[100:101] op_sel_hi:[1,0]
	s_nop 0
	v_pk_fma_f32 v[12:13], v[16:17], v[22:23], v[12:13]
	v_mov_b64_e32 v[22:23], v[164:165]
	v_mov_b64_e32 v[24:25], v[166:167]
	v_mov_b64_e32 v[26:27], v[160:161]
	v_mov_b64_e32 v[28:29], v[162:163]
	s_waitcnt vmcnt(1)
	v_pk_fma_f32 v[34:35], v[22:23], v[34:35], v[98:99]
	s_waitcnt vmcnt(0)
	v_pk_fma_f32 v[30:31], v[26:27], v[30:31], v[92:93]
	v_fma_f32 v92, -v65, v59, v55
	v_cmp_ge_f32_e64 s[4:5], 0, v92
	v_add_u32_e32 v92, 1, v59
	v_pk_fma_f32 v[32:33], v[28:29], v[32:33], v[94:95]
	v_cndmask_b32_e64 v65, v59, v65, s[4:5]
	v_fma_f32 v59, -v92, v59, v55
	v_cmp_lt_f32_e64 s[4:5], 0, v59
	v_pk_fma_f32 v[36:37], v[24:25], v[36:37], v[96:97]
	s_nop 0
	v_cndmask_b32_e64 v59, v65, v92, s[4:5]
	v_mul_f32_e32 v65, 0x37800000, v59
	v_cndmask_b32_e32 v59, v59, v65, vcc
	v_cmp_class_f32_e32 vcc, v55, v243
	s_nop 1
	v_cndmask_b32_e32 v55, v59, v55, vcc
	v_div_scale_f32 v59, s[4:5], v55, v55, 1.0
	v_rcp_f32_e32 v65, v59
	s_mov_b64 s[4:5], -1
	v_fma_f32 v92, -v59, v65, 1.0
	v_fmac_f32_e32 v65, v92, v65
	v_div_scale_f32 v92, vcc, 1.0, v55, 1.0
	v_mul_f32_e32 v93, v92, v65
	v_fma_f32 v94, -v59, v93, v92
	v_fmac_f32_e32 v93, v94, v65
	v_fma_f32 v59, -v59, v93, v92
	v_div_fmas_f32 v59, v59, v65, v93
	v_div_fixup_f32 v92, v59, v55, 1.0
	v_pk_mul_f32 v[68:69], v[68:69], v[92:93] op_sel_hi:[1,0]
	s_andn2_b64 vcc, exec, s[34:35]
	v_pk_fma_f32 v[18:19], v[18:19], v[68:69], v[84:85]
	v_pk_mul_f32 v[68:69], v[70:71], v[92:93] op_sel_hi:[1,0]
	v_pk_mul_f32 v[70:71], v[82:83], v[92:93] op_sel_hi:[1,0]
	v_pk_fma_f32 v[20:21], v[20:21], v[68:69], v[86:87]
	v_pk_mul_f32 v[68:69], v[72:73], v[92:93] op_sel_hi:[1,0]
	s_nop 0
	v_pk_fma_f32 v[14:15], v[14:15], v[68:69], v[88:89]
	v_pk_mul_f32 v[68:69], v[74:75], v[92:93] op_sel_hi:[1,0]
	s_nop 0
	v_pk_fma_f32 v[16:17], v[16:17], v[68:69], v[90:91]
	v_lshlrev_b32_e32 v68, 16, v2
	v_and_b32_e32 v69, 0xffff0000, v2
	v_pk_fma_f32 v[26:27], v[26:27], v[70:71], v[68:69]
	v_lshlrev_b32_e32 v2, 16, v3
	v_and_b32_e32 v3, 0xffff0000, v3
	v_pk_mul_f32 v[68:69], v[80:81], v[92:93] op_sel_hi:[1,0]
	s_nop 0
	v_pk_fma_f32 v[28:29], v[28:29], v[68:69], v[2:3]
	v_lshlrev_b32_e32 v2, 16, v4
	v_and_b32_e32 v3, 0xffff0000, v4
	v_pk_mul_f32 v[68:69], v[78:79], v[92:93] op_sel_hi:[1,0]
	v_lshlrev_b32_e32 v4, 16, v5
	v_pk_fma_f32 v[2:3], v[22:23], v[68:69], v[2:3]
	v_and_b32_e32 v5, 0xffff0000, v5
	v_pk_mul_f32 v[22:23], v[76:77], v[92:93] op_sel_hi:[1,0]
	s_nop 0
	v_pk_fma_f32 v[4:5], v[24:25], v[22:23], v[4:5]
	s_cbranch_vccnz .LBB0_816
	v_mad_i32_i24 v23, v58, s84, v38
	v_cmp_lt_i32_e32 vcc, 15, v23
	v_lshlrev_b32_e32 v22, 2, v40
	s_and_saveexec_b64 s[4:5], vcc
	s_cbranch_execz .LBB0_813
	v_ashrrev_i32_e32 v59, 31, v58
	v_add_u32_e32 v24, -16, v23
	v_mov_b32_e32 v25, v0
	v_lshlrev_b64 v[58:59], 23, v[58:59]
	v_lshl_add_u64 v[58:59], s[8:9], 0, v[58:59]
	v_lshlrev_b64 v[24:25], 12, v[24:25]
	v_lshl_add_u64 v[24:25], v[58:59], 0, v[24:25]
	v_mov_b32_e32 v23, v0
	v_lshl_add_u64 v[24:25], v[24:25], 0, v[22:23]
	global_store_dwordx4 v[24:25], v[6:9], off nt
	global_store_dwordx4 v[24:25], v[10:13], off offset:16 nt
	global_store_dwordx4 v[24:25], v[30:33], off offset:2048 nt
	global_store_dwordx4 v[24:25], v[34:37], off offset:2064 nt
